# v70 + diff loop: K-fragment ds_reads issued first after the barrier, far/init math moved behind them
# baseline (speedup 1.0000x reference)
; #define MFMA32(a, b, c) __builtin_amdgcn_mfma_f32_32x32x16_bf16((a), (b), (c), 0, 0, 0)
; template <int DQK, int KROW, bool BIAS, bool MAPS2>
; DI void attn_core(const int t, const u16* __restrict__ Q, int ldq, const u16* __restrict__ Kp, int ldk, const u16* __restrict__ Vt, int q0,
;                   char* lds, const float* lut, float b31, f32x16 (&o)[4], float& l_out) {
;     ...
;     const bool live = (kt << 6) <= wq0 + 31;
;     if (live) {
;       const int k0 = kt << 6;
;       const bool far = BIAS && (wq0 - (k0 + 63) >= 128);
;       const float init = (far ? b31 : 0.f) - m_run;
; #pragma unroll
;       for (int k2 = 0; k2 < 2; ++k2)
; #pragma unroll
;         for (int i = 0; i < 16; ++i) s[k2][i] = init;
;       {
;         constexpr int QBS = (NKS > 4) ? 2 : 4, NBT = NKS / QBS;
;         bf16x8 kfb[2][QBS][2];
;         const char* kbase = lds + (kt & 1) * AT_KBUF + r * KS + hf * 16 + map * (DQK * 2);
; #pragma unroll
;         for (int jq = 0; jq < QBS; ++jq)
; #pragma unroll
;           for (int k2 = 0; k2 < 2; ++k2) kfb[0][jq][k2] = *(const bf16x8*)(kbase + 32 * k2 * KS + jq * 32);
; #pragma unroll
;         for (int b = 0; b < NBT; ++b) {
;           if (b + 1 < NBT) {
; #pragma unroll
;             for (int jq = 0; jq < QBS; ++jq)
; #pragma unroll
;               for (int k2 = 0; k2 < 2; ++k2) kfb[(b + 1) & 1][jq][k2] = *(const bf16x8*)(kbase + 32 * k2 * KS + ((b + 1) * QBS + jq) * 32);
;           }
;           __builtin_amdgcn_sched_barrier(0);
;           __builtin_amdgcn_s_setprio(1);
; #pragma unroll
;           for (int jq = 0; jq < QBS; ++jq)
; #pragma unroll
;             for (int k2 = 0; k2 < 2; ++k2) s[k2] = MFMA32(kfb[b & 1][jq][k2], qf[b * QBS + jq], s[k2]);
;           __builtin_amdgcn_s_setprio(0);
;           __builtin_amdgcn_sched_barrier(0);
;         }
;       }
;       if (BIAS && !far) {
; #pragma unroll
;         for (int k2 = 0; k2 < 2; ++k2)
; #pragma unroll
;           for (int i = 0; i < 16; ++i) {
;             const int key = k0 + 32 * k2 + (i & 3) + 8 * (i >> 2) + 4 * hf;
;             int d = qrow - key; d = d < 0 ? 0 : (d > 128 ? 128 : d);
;             s[k2][i] += lut[d];
;           }
;       }
.LBB0_235:
	v_cmp_le_i32_e32 vcc, s90, v155
	s_and_saveexec_b64 s[92:93], vcc
	s_cbranch_execz .LBB0_243
	s_and_b32 s91, s96, 1
	s_mul_i32 s0, s91, 0x6400
	v_add_u32_e32 v186, s0, v156
	ds_read_b128 v[2:5], v186 offset:8704
	ds_read_b128 v[6:9], v186
	ds_read_b128 v[10:13], v186 offset:32
	ds_read_b128 v[162:165], v186 offset:8736
	ds_read_b128 v[166:169], v186 offset:64
	ds_read_b128 v[170:173], v186 offset:8768
	ds_read_b128 v[174:177], v186 offset:96
	ds_read_b128 v[178:181], v186 offset:8800
	s_movk_i32 s0, 0x80
	v_cmp_gt_i32_e32 vcc, s0, v159
	s_movk_i32 s0, 0x7f
	v_cmp_lt_i32_e64 s[0:1], s0, v159
	s_nop 1
	v_cndmask_b32_e64 v0, 0, v152, s[0:1]
	v_sub_f32_e32 v80, v0, v161
	s_setprio 1
	v_mov_b32_e32 v81, v80
	v_mov_b32_e32 v82, v80
	v_mov_b32_e32 v83, v80
	v_mov_b32_e32 v84, v80
	v_mov_b32_e32 v85, v80
	v_mov_b32_e32 v86, v80
	v_mov_b32_e32 v87, v80
	v_mov_b32_e32 v88, v80
	v_mov_b32_e32 v89, v80
	v_mov_b32_e32 v90, v80
	v_mov_b32_e32 v91, v80
	v_mov_b32_e32 v92, v80
	v_mov_b32_e32 v93, v80
	v_mov_b32_e32 v94, v80
	v_mov_b32_e32 v95, v80
	s_waitcnt lgkmcnt(6)
	s_nop 0
	v_mfma_f32_32x32x16_bf16 v[96:111], v[6:9], v[112:115], v[80:95]
	v_mfma_f32_32x32x16_bf16 v[80:95], v[2:5], v[112:115], v[80:95]
	s_waitcnt lgkmcnt(5)
	v_mfma_f32_32x32x16_bf16 v[96:111], v[10:13], v[116:119], v[96:111]
	s_waitcnt lgkmcnt(4)
	v_mfma_f32_32x32x16_bf16 v[80:95], v[162:165], v[116:119], v[80:95]
	s_waitcnt lgkmcnt(3)
	v_mfma_f32_32x32x16_bf16 v[96:111], v[166:169], v[120:123], v[96:111]
	s_waitcnt lgkmcnt(2)
	v_mfma_f32_32x32x16_bf16 v[80:95], v[170:173], v[120:123], v[80:95]
	s_waitcnt lgkmcnt(1)
	v_mfma_f32_32x32x16_bf16 v[96:111], v[174:177], v[124:127], v[96:111]
	s_waitcnt lgkmcnt(0)
	v_mfma_f32_32x32x16_bf16 v[80:95], v[178:181], v[124:127], v[80:95]
	s_setprio 0
	s_and_saveexec_b64 s[0:1], vcc
	s_cbranch_execz .LBB0_238
	v_add_u32_e32 v0, v160, v159
	v_lshlrev_b32_e32 v0, 2, v0
	v_add_u32_e32 v0, 0x16178, v0
	ds_read2_b32 v[2:3], v0 offset0:63 offset1:62
	ds_read2_b32 v[4:5], v0 offset0:61 offset1:60
	ds_read2_b32 v[6:7], v0 offset0:55 offset1:54
	ds_read2_b32 v[8:9], v0 offset0:53 offset1:52
	ds_read2_b32 v[10:11], v0 offset0:47 offset1:46
	ds_read2_b32 v[12:13], v0 offset0:45 offset1:44
	ds_read2_b32 v[14:15], v0 offset0:39 offset1:38
	ds_read2_b32 v[162:163], v0 offset0:37 offset1:36
	ds_read2_b32 v[164:165], v0 offset0:31 offset1:30
	ds_read2_b32 v[166:167], v0 offset0:29 offset1:28
	ds_read2_b32 v[168:169], v0 offset0:23 offset1:22
	ds_read2_b32 v[170:171], v0 offset0:21 offset1:20
	ds_read2_b32 v[172:173], v0 offset0:15 offset1:14
	ds_read2_b32 v[174:175], v0 offset0:13 offset1:12
	ds_read2_b32 v[176:177], v0 offset0:7 offset1:6
	ds_read2_b32 v[178:179], v0 offset0:5 offset1:4
	s_waitcnt lgkmcnt(8)
	v_pk_add_f32 v[108:109], v[108:109], v[14:15]
	v_pk_add_f32 v[110:111], v[110:111], v[162:163]
	v_pk_add_f32 v[106:107], v[106:107], v[12:13]
	v_pk_add_f32 v[104:105], v[104:105], v[10:11]
	v_pk_add_f32 v[102:103], v[102:103], v[8:9]
	v_pk_add_f32 v[100:101], v[100:101], v[6:7]
	v_pk_add_f32 v[98:99], v[98:99], v[4:5]
	v_pk_add_f32 v[96:97], v[96:97], v[2:3]
	s_waitcnt lgkmcnt(0)
	v_pk_add_f32 v[94:95], v[94:95], v[178:179]
	v_pk_add_f32 v[92:93], v[92:93], v[176:177]
	v_pk_add_f32 v[90:91], v[90:91], v[174:175]
	v_pk_add_f32 v[88:89], v[88:89], v[172:173]
	v_pk_add_f32 v[86:87], v[86:87], v[170:171]
	v_pk_add_f32 v[84:85], v[84:85], v[168:169]
	v_pk_add_f32 v[82:83], v[82:83], v[166:167]
	v_pk_add_f32 v[80:81], v[80:81], v[164:165]
